# conv1 (deferred weight/cache conversion inside layer-0 GEMM1) output stores switched to nt so they do not displace GEMM operands in L2/Infinity Cache, on top of v12
# speedup vs baseline: 1.0007x; 1.0007x over previous
.LBB0_176:
	s_or_b64 exec, exec, s[6:7]
	v_readlane_b32 s8, v253, 52
	s_lshl_b32 s6, s22, 6
	v_readlane_b32 s9, v253, 53
	v_or_b32_e32 v17, s6, v35
	s_mov_b32 s7, 0xb940
	v_mov_b64_e32 v[18:19], s[8:9]
	v_mad_i64_i32 v[18:19], s[8:9], v17, s7, v[18:19]
	v_ashrrev_i32_e32 v17, 31, v16
	s_waitcnt vmcnt(10)
	v_lshl_add_u64 v[108:109], v[16:17], 2, v[18:19]
	v_add_co_u32_e32 v20, vcc, 0xb000, v108
	s_ashr_i32 s7, s6, 31
	s_nop 0
	v_addc_co_u32_e32 v21, vcc, 0, v109, vcc
	v_add_co_u32_e32 v24, vcc, 0x17000, v108
	global_load_dwordx4 v[16:19], v[108:109], off nt
	s_nop 0
	global_load_dwordx4 v[20:23], v[20:21], off offset:2368 nt
	v_addc_co_u32_e32 v25, vcc, 0, v109, vcc
	v_add_co_u32_e32 v28, vcc, 0x22000, v108
	s_nop 1
	v_addc_co_u32_e32 v29, vcc, 0, v109, vcc
	v_add_co_u32_e32 v68, vcc, 0x2e000, v108
	global_load_dwordx4 v[24:27], v[24:25], off offset:640 nt
	s_nop 0
	global_load_dwordx4 v[28:31], v[28:29], off offset:3008 nt
	v_addc_co_u32_e32 v69, vcc, 0, v109, vcc
	s_waitcnt vmcnt(5)
	v_add_co_u32_e32 v72, vcc, 0x39000, v108
	s_nop 1
	v_addc_co_u32_e32 v73, vcc, 0, v109, vcc
	v_add_co_u32_e32 v76, vcc, 0x45000, v108
	global_load_dwordx4 v[68:71], v[68:69], off offset:1280 nt
	s_nop 0
	global_load_dwordx4 v[72:75], v[72:73], off offset:3648 nt
	v_addc_co_u32_e32 v77, vcc, 0, v109, vcc
	v_add_co_u32_e32 v80, vcc, 0x51000, v108
	s_nop 1
	v_addc_co_u32_e32 v81, vcc, 0, v109, vcc
	v_add_co_u32_e32 v84, vcc, 0x5c000, v108
	global_load_dwordx4 v[76:79], v[76:77], off offset:1920 nt
	s_nop 0
	global_load_dwordx4 v[80:83], v[80:81], off offset:192 nt
	v_addc_co_u32_e32 v85, vcc, 0, v109, vcc
	v_add_co_u32_e32 v88, vcc, 0x68000, v108
	s_nop 1
	v_addc_co_u32_e32 v89, vcc, 0, v109, vcc
	v_add_co_u32_e32 v92, vcc, 0x73000, v108
	global_load_dwordx4 v[84:87], v[84:85], off offset:2560 nt
	s_nop 0
	global_load_dwordx4 v[88:91], v[88:89], off offset:832 nt
	v_addc_co_u32_e32 v93, vcc, 0, v109, vcc
	v_add_co_u32_e32 v96, vcc, 0x7f000, v108
	s_nop 1
	v_addc_co_u32_e32 v97, vcc, 0, v109, vcc
	v_add_co_u32_e32 v100, vcc, 0x8a000, v108
	global_load_dwordx4 v[92:95], v[92:93], off offset:3200 nt
	s_nop 0
	global_load_dwordx4 v[96:99], v[96:97], off offset:1472 nt
	v_addc_co_u32_e32 v101, vcc, 0, v109, vcc
	v_add_co_u32_e32 v104, vcc, 0x96000, v108
	s_nop 1
	v_addc_co_u32_e32 v105, vcc, 0, v109, vcc
	v_add_co_u32_e32 v110, vcc, 0xa2000, v108
	global_load_dwordx4 v[100:103], v[100:101], off offset:3840 nt
	s_nop 0
	global_load_dwordx4 v[104:107], v[104:105], off offset:2112 nt
	v_addc_co_u32_e32 v111, vcc, 0, v109, vcc
	v_add_co_u32_e32 v112, vcc, 0xad000, v108
	s_nop 1
	v_addc_co_u32_e32 v113, vcc, 0, v109, vcc
	global_load_dwordx4 v[108:111], v[110:111], off offset:384 nt
	s_nop 0
	global_load_dwordx4 v[112:115], v[112:113], off offset:2752 nt
	s_waitcnt vmcnt(14)
	v_cvt_pk_bf16_f32 v116, v16, v20
	s_waitcnt vmcnt(12)
	v_cvt_pk_bf16_f32 v117, v24, v28
	s_waitcnt vmcnt(10)
	v_cvt_pk_bf16_f32 v118, v68, v72
	s_waitcnt vmcnt(8)
	v_cvt_pk_bf16_f32 v119, v76, v80
	v_add_u32_e32 v24, v38, v36
	v_add_u32_e32 v28, v38, v37
	s_waitcnt vmcnt(6)
	v_cvt_pk_bf16_f32 v120, v84, v88
	s_waitcnt vmcnt(4)
	v_cvt_pk_bf16_f32 v121, v92, v96
	s_waitcnt vmcnt(2)
	v_cvt_pk_bf16_f32 v122, v100, v104
	s_waitcnt vmcnt(0)
	v_cvt_pk_bf16_f32 v123, v108, v112
	ds_write_b128 v24, v[116:119]
	ds_write_b128 v28, v[120:123]
	v_cvt_pk_bf16_f32 v116, v17, v21
	v_cvt_pk_bf16_f32 v117, v25, v29
	v_cvt_pk_bf16_f32 v118, v69, v73
	v_cvt_pk_bf16_f32 v119, v77, v81
	v_cvt_pk_bf16_f32 v120, v85, v89
	v_cvt_pk_bf16_f32 v121, v93, v97
	v_cvt_pk_bf16_f32 v122, v101, v105
	v_cvt_pk_bf16_f32 v123, v109, v113
	ds_write_b128 v24, v[116:119] offset:128
	ds_write_b128 v28, v[120:123] offset:128
	v_cvt_pk_bf16_f32 v116, v18, v22
	v_cvt_pk_bf16_f32 v117, v26, v30
	v_cvt_pk_bf16_f32 v118, v70, v74
	v_cvt_pk_bf16_f32 v119, v78, v82
	v_cvt_pk_bf16_f32 v120, v86, v90
	v_cvt_pk_bf16_f32 v121, v94, v98
	v_cvt_pk_bf16_f32 v122, v102, v106
	v_cvt_pk_bf16_f32 v123, v110, v114
	ds_write_b128 v24, v[116:119] offset:256
	ds_write_b128 v28, v[120:123] offset:256
	v_cvt_pk_bf16_f32 v16, v19, v23
	v_cvt_pk_bf16_f32 v17, v27, v31
	v_cvt_pk_bf16_f32 v18, v71, v75
	v_cvt_pk_bf16_f32 v19, v79, v83
	v_cvt_pk_bf16_f32 v20, v87, v91
	v_cvt_pk_bf16_f32 v21, v95, v99
	v_cvt_pk_bf16_f32 v22, v103, v107
	v_cvt_pk_bf16_f32 v23, v111, v115
	ds_write_b128 v24, v[16:19] offset:384
	ds_write_b128 v28, v[20:23] offset:384
	s_waitcnt lgkmcnt(0)
	v_add_u32_e32 v16, v39, v40
	ds_read_b128 v[16:19], v16
	v_or_b32_e32 v20, s21, v5
	v_ashrrev_i32_e32 v21, 31, v20
	v_lshl_add_u64 v[24:25], s[6:7], 1, v[14:15]
	v_lshlrev_b64 v[20:21], 13, v[20:21]
	v_lshl_add_u64 v[26:27], v[24:25], 0, v[20:21]
	v_add_u32_e32 v20, v41, v42
	ds_read_b128 v[20:23], v20
	s_waitcnt lgkmcnt(1)
	global_store_dwordx4 v[26:27], v[16:19], off nt
	s_nop 1
	v_or_b32_e32 v16, s21, v9
	v_ashrrev_i32_e32 v17, 31, v16
	v_lshlrev_b64 v[16:17], 13, v[16:17]
	v_lshl_add_u64 v[16:17], v[24:25], 0, v[16:17]
	s_waitcnt lgkmcnt(0)
	global_store_dwordx4 v[16:17], v[20:23], off nt
	v_add_u32_e32 v16, v43, v44
	ds_read_b128 v[16:19], v16
	v_or_b32_e32 v20, s21, v11
	v_ashrrev_i32_e32 v21, 31, v20
	v_lshlrev_b64 v[20:21], 13, v[20:21]
	v_lshl_add_u64 v[26:27], v[24:25], 0, v[20:21]
	v_add_u32_e32 v20, v45, v46
	ds_read_b128 v[20:23], v20
	s_waitcnt lgkmcnt(1)
	global_store_dwordx4 v[26:27], v[16:19], off nt
	s_nop 1
	v_or_b32_e32 v16, s21, v32
	v_ashrrev_i32_e32 v17, 31, v16
	v_lshlrev_b64 v[16:17], 13, v[16:17]
	v_lshl_add_u64 v[16:17], v[24:25], 0, v[16:17]
	s_waitcnt lgkmcnt(0)
	global_store_dwordx4 v[16:17], v[20:23], off nt
	v_add_u32_e32 v16, v48, v40
	ds_read_b128 v[16:19], v16
	v_or_b32_e32 v20, s21, v47
	v_ashrrev_i32_e32 v21, 31, v20
	v_lshlrev_b64 v[20:21], 13, v[20:21]
	v_lshl_add_u64 v[26:27], v[24:25], 0, v[20:21]
	v_add_u32_e32 v20, v50, v51
	ds_read_b128 v[20:23], v20
	s_waitcnt lgkmcnt(1)
	global_store_dwordx4 v[26:27], v[16:19], off nt
	s_nop 1
	v_or_b32_e32 v16, s21, v49
	v_ashrrev_i32_e32 v17, 31, v16
	v_lshlrev_b64 v[16:17], 13, v[16:17]
	v_lshl_add_u64 v[16:17], v[24:25], 0, v[16:17]
	s_waitcnt lgkmcnt(0)
	global_store_dwordx4 v[16:17], v[20:23], off nt
	v_add_u32_e32 v16, v53, v54
	ds_read_b128 v[16:19], v16
	v_or_b32_e32 v20, s21, v52
	v_ashrrev_i32_e32 v21, 31, v20
	v_lshlrev_b64 v[20:21], 13, v[20:21]
	v_lshl_add_u64 v[26:27], v[24:25], 0, v[20:21]
	v_add_u32_e32 v20, v56, v57
	ds_read_b128 v[20:23], v20
	s_waitcnt lgkmcnt(1)
	global_store_dwordx4 v[26:27], v[16:19], off nt
	s_nop 1
	v_or_b32_e32 v16, s21, v55
	v_ashrrev_i32_e32 v17, 31, v16
	v_lshlrev_b64 v[16:17], 13, v[16:17]
	v_lshl_add_u64 v[16:17], v[24:25], 0, v[16:17]
	s_waitcnt lgkmcnt(0)
	global_store_dwordx4 v[16:17], v[20:23], off nt
	s_waitcnt lgkmcnt(0)

.LBB0_202:
	s_waitcnt lgkmcnt(0)
	ds_read2_b32 v[18:19], v7 offset1:33
	s_waitcnt lgkmcnt(0)
	v_cvt_pk_bf16_f32 v18, v18, v19
	ds_read2_b32 v[20:21], v7 offset0:66 offset1:99
	s_waitcnt lgkmcnt(0)
	v_cvt_pk_bf16_f32 v19, v20, v21
	ds_read2_b32 v[20:21], v7 offset0:132 offset1:165
	s_lshl_b32 s6, s22, 7
	v_readlane_b32 s8, v254, 28
	s_waitcnt lgkmcnt(0)
	v_cvt_pk_bf16_f32 v20, v20, v21
	ds_read2_b32 v[22:23], v7 offset0:198 offset1:231
	v_readlane_b32 s9, v254, 29
	s_and_b32 s8, s6, 0x3f80
	s_waitcnt lgkmcnt(0)
	v_cvt_pk_bf16_f32 v21, v22, v23
	v_or_b32_e32 v22, s21, v5
	v_lshl_add_u64 v[16:17], v[12:13], 0, s[8:9]
	v_lshlrev_b32_e32 v22, 13, v22
	v_mov_b32_e32 v23, v4
	v_lshl_add_u64 v[22:23], v[16:17], 0, v[22:23]
	global_store_dwordx4 v[22:23], v[18:21], off nt
	ds_read2_b32 v[18:19], v7 offset0:8 offset1:41
	s_mov_b32 s7, s9
	s_waitcnt lgkmcnt(0)
	v_cvt_pk_bf16_f32 v18, v18, v19
	ds_read2_b32 v[20:21], v7 offset0:74 offset1:107
	s_waitcnt lgkmcnt(0)
	v_cvt_pk_bf16_f32 v19, v20, v21
	ds_read2_b32 v[20:21], v7 offset0:140 offset1:173
	s_waitcnt lgkmcnt(0)
	v_cvt_pk_bf16_f32 v20, v20, v21
	ds_read2_b32 v[22:23], v7 offset0:206 offset1:239
	s_waitcnt lgkmcnt(0)
	v_cvt_pk_bf16_f32 v21, v22, v23
	v_or_b32_e32 v22, s21, v9
	v_lshlrev_b32_e32 v22, 13, v22
	v_mov_b32_e32 v23, v4
	v_lshl_add_u64 v[22:23], v[16:17], 0, v[22:23]
	global_store_dwordx4 v[22:23], v[18:21], off nt
	ds_read2_b32 v[18:19], v7 offset0:16 offset1:49
	v_writelane_b32 v254, s6, 28
	s_waitcnt lgkmcnt(0)
	v_cvt_pk_bf16_f32 v18, v18, v19
	ds_read2_b32 v[20:21], v7 offset0:82 offset1:115
	s_waitcnt lgkmcnt(0)
	v_cvt_pk_bf16_f32 v19, v20, v21
	ds_read2_b32 v[20:21], v7 offset0:148 offset1:181
	s_waitcnt lgkmcnt(0)
	v_cvt_pk_bf16_f32 v20, v20, v21
	ds_read2_b32 v[22:23], v7 offset0:214 offset1:247
	s_waitcnt lgkmcnt(0)
	v_cvt_pk_bf16_f32 v21, v22, v23
	v_or_b32_e32 v22, s21, v11
	v_lshlrev_b32_e32 v22, 13, v22
	v_mov_b32_e32 v23, v4
	v_lshl_add_u64 v[22:23], v[16:17], 0, v[22:23]
	global_store_dwordx4 v[22:23], v[18:21], off nt
	ds_read2_b32 v[18:19], v7 offset0:24 offset1:57
	v_writelane_b32 v254, s7, 29
	s_waitcnt lgkmcnt(0)
	v_cvt_pk_bf16_f32 v18, v18, v19
	ds_read2_b32 v[20:21], v7 offset0:90 offset1:123
	s_waitcnt lgkmcnt(0)
	v_cvt_pk_bf16_f32 v19, v20, v21
	ds_read2_b32 v[20:21], v7 offset0:156 offset1:189
	s_waitcnt lgkmcnt(0)
	v_cvt_pk_bf16_f32 v20, v20, v21
	ds_read2_b32 v[22:23], v7 offset0:222 offset1:255
	s_waitcnt lgkmcnt(0)
	v_cvt_pk_bf16_f32 v21, v22, v23
	v_or_b32_e32 v22, s21, v32
	v_lshlrev_b32_e32 v22, 13, v22
	v_mov_b32_e32 v23, v4
	v_lshl_add_u64 v[16:17], v[16:17], 0, v[22:23]
	global_store_dwordx4 v[16:17], v[18:21], off nt
	s_waitcnt lgkmcnt(0)
	s_mov_b64 s[6:7], 0

.LBB0_205:
	s_lshl_b32 s27, s24, 1
	s_lshl_b32 s26, s22, 1
	v_or_b32_e32 v22, s27, v6
	v_or_b32_e32 v17, s26, v1
	v_add_u32_e32 v20, s8, v22
	v_add_u32_e32 v18, s23, v17
	v_mad_u64_u32 v[20:21], s[28:29], v20, s31, v[16:17]
	v_mad_u64_u32 v[18:19], s[28:29], v18, s31, v[16:17]
	v_mov_b32_e32 v21, v4
	v_lshl_add_u64 v[20:21], v[20:21], 2, s[6:7]
	v_mov_b32_e32 v19, v4
	v_lshl_add_u64 v[18:19], v[18:19], 2, s[6:7]
	global_load_dword v72, v[20:21], off
	global_load_dword v73, v[18:19], off
	v_mad_u64_u32 v[18:19], s[28:29], v22, s30, v[8:9]
	v_mad_u64_u32 v[20:21], s[28:29], v17, s30, v[8:9]
	s_add_i32 s29, s27, 4
	s_add_i32 s28, s26, 4
	v_or_b32_e32 v22, s29, v6
	v_or_b32_e32 v17, s28, v1
	s_add_i32 s24, s24, 16
	s_add_i32 s22, s22, 16
	s_add_i32 s25, s25, -16
	v_mov_b32_e32 v74, v18
	v_mov_b32_e32 v75, v20
	v_add_u32_e32 v20, s8, v22
	v_add_u32_e32 v18, s23, v17
	v_mad_u64_u32 v[20:21], s[28:29], v20, s31, v[16:17]
	v_mad_u64_u32 v[18:19], s[28:29], v18, s31, v[16:17]
	v_mov_b32_e32 v21, v4
	v_lshl_add_u64 v[20:21], v[20:21], 2, s[6:7]
	v_mov_b32_e32 v19, v4
	v_lshl_add_u64 v[18:19], v[18:19], 2, s[6:7]
	global_load_dword v76, v[20:21], off
	global_load_dword v77, v[18:19], off
	v_mad_u64_u32 v[18:19], s[28:29], v22, s30, v[8:9]
	v_mad_u64_u32 v[20:21], s[28:29], v17, s30, v[8:9]
	s_add_i32 s29, s27, 8
	s_add_i32 s28, s26, 8
	v_or_b32_e32 v22, s29, v6
	v_or_b32_e32 v17, s28, v1
	v_mov_b32_e32 v78, v18
	v_mov_b32_e32 v79, v20
	v_add_u32_e32 v20, s8, v22
	v_add_u32_e32 v18, s23, v17
	v_mad_u64_u32 v[20:21], s[28:29], v20, s31, v[16:17]
	v_mad_u64_u32 v[18:19], s[28:29], v18, s31, v[16:17]
	v_mov_b32_e32 v21, v4
	v_lshl_add_u64 v[20:21], v[20:21], 2, s[6:7]
	v_mov_b32_e32 v19, v4
	v_lshl_add_u64 v[18:19], v[18:19], 2, s[6:7]
	global_load_dword v80, v[20:21], off
	global_load_dword v81, v[18:19], off
	v_mad_u64_u32 v[18:19], s[28:29], v22, s30, v[8:9]
	v_mad_u64_u32 v[20:21], s[28:29], v17, s30, v[8:9]
	s_add_i32 s29, s27, 12
	s_add_i32 s28, s26, 12
	v_or_b32_e32 v22, s29, v6
	v_or_b32_e32 v17, s28, v1
	v_mov_b32_e32 v82, v18
	v_mov_b32_e32 v83, v20
	v_add_u32_e32 v20, s8, v22
	v_add_u32_e32 v18, s23, v17
	v_mad_u64_u32 v[20:21], s[28:29], v20, s31, v[16:17]
	v_mad_u64_u32 v[18:19], s[28:29], v18, s31, v[16:17]
	v_mov_b32_e32 v21, v4
	v_lshl_add_u64 v[20:21], v[20:21], 2, s[6:7]
	v_mov_b32_e32 v19, v4
	v_lshl_add_u64 v[18:19], v[18:19], 2, s[6:7]
	global_load_dword v84, v[20:21], off
	global_load_dword v85, v[18:19], off
	v_mad_u64_u32 v[18:19], s[28:29], v22, s30, v[8:9]
	v_mad_u64_u32 v[20:21], s[28:29], v17, s30, v[8:9]
	s_add_i32 s29, s27, 16
	s_add_i32 s28, s26, 16
	v_or_b32_e32 v22, s29, v6
	v_or_b32_e32 v17, s28, v1
	v_mov_b32_e32 v86, v18
	v_mov_b32_e32 v87, v20
	v_add_u32_e32 v20, s8, v22
	v_add_u32_e32 v18, s23, v17
	v_mad_u64_u32 v[20:21], s[28:29], v20, s31, v[16:17]
	v_mad_u64_u32 v[18:19], s[28:29], v18, s31, v[16:17]
	v_mov_b32_e32 v21, v4
	v_lshl_add_u64 v[20:21], v[20:21], 2, s[6:7]
	v_mov_b32_e32 v19, v4
	v_lshl_add_u64 v[18:19], v[18:19], 2, s[6:7]
	global_load_dword v88, v[20:21], off
	global_load_dword v89, v[18:19], off
	v_mad_u64_u32 v[18:19], s[28:29], v22, s30, v[8:9]
	v_mad_u64_u32 v[20:21], s[28:29], v17, s30, v[8:9]
	s_add_i32 s29, s27, 20
	s_add_i32 s28, s26, 20
	v_or_b32_e32 v22, s29, v6
	v_or_b32_e32 v17, s28, v1
	v_mov_b32_e32 v90, v18
	v_mov_b32_e32 v91, v20
	v_add_u32_e32 v20, s8, v22
	v_add_u32_e32 v18, s23, v17
	v_mad_u64_u32 v[20:21], s[28:29], v20, s31, v[16:17]
	v_mad_u64_u32 v[18:19], s[28:29], v18, s31, v[16:17]
	v_mov_b32_e32 v21, v4
	v_lshl_add_u64 v[20:21], v[20:21], 2, s[6:7]
	v_mov_b32_e32 v19, v4
	v_lshl_add_u64 v[18:19], v[18:19], 2, s[6:7]
	global_load_dword v92, v[20:21], off
	global_load_dword v93, v[18:19], off
	v_mad_u64_u32 v[18:19], s[28:29], v22, s30, v[8:9]
	v_mad_u64_u32 v[20:21], s[28:29], v17, s30, v[8:9]
	s_add_i32 s29, s27, 24
	s_add_i32 s28, s26, 24
	v_or_b32_e32 v22, s29, v6
	v_or_b32_e32 v17, s28, v1
	s_add_i32 s27, s27, 28
	s_add_i32 s26, s26, 28
	s_cmp_lg_u32 s25, 0
	v_mov_b32_e32 v94, v18
	v_mov_b32_e32 v95, v20
	v_add_u32_e32 v20, s8, v22
	v_add_u32_e32 v18, s23, v17
	v_mad_u64_u32 v[20:21], s[28:29], v20, s31, v[16:17]
	v_mad_u64_u32 v[18:19], s[28:29], v18, s31, v[16:17]
	v_mov_b32_e32 v21, v4
	v_lshl_add_u64 v[20:21], v[20:21], 2, s[6:7]
	v_mov_b32_e32 v19, v4
	v_lshl_add_u64 v[18:19], v[18:19], 2, s[6:7]
	global_load_dword v96, v[20:21], off
	global_load_dword v97, v[18:19], off
	v_mad_u64_u32 v[18:19], s[28:29], v22, s30, v[8:9]
	v_mad_u64_u32 v[20:21], s[28:29], v17, s30, v[8:9]
	v_or_b32_e32 v22, s27, v6
	v_or_b32_e32 v17, s26, v1
	v_mov_b32_e32 v98, v18
	v_mov_b32_e32 v99, v20
	v_add_u32_e32 v20, s8, v22
	v_add_u32_e32 v18, s23, v17
	v_mad_u64_u32 v[20:21], s[26:27], v20, s31, v[16:17]
	v_mad_u64_u32 v[18:19], s[26:27], v18, s31, v[16:17]
	v_mov_b32_e32 v21, v4
	v_lshl_add_u64 v[20:21], v[20:21], 2, s[6:7]
	v_mov_b32_e32 v19, v4
	v_lshl_add_u64 v[18:19], v[18:19], 2, s[6:7]
	global_load_dword v100, v[20:21], off
	global_load_dword v101, v[18:19], off
	v_mad_u64_u32 v[18:19], s[26:27], v22, s30, v[8:9]
	v_mad_u64_u32 v[20:21], s[26:27], v17, s30, v[8:9]
	v_mov_b32_e32 v102, v18
	v_mov_b32_e32 v103, v20
	s_waitcnt vmcnt(0)
	ds_write_b32 v74, v72
	ds_write_b32 v75, v73
	ds_write_b32 v78, v76
	ds_write_b32 v79, v77
	ds_write_b32 v82, v80
	ds_write_b32 v83, v81
	ds_write_b32 v86, v84
	ds_write_b32 v87, v85
	ds_write_b32 v90, v88
	ds_write_b32 v91, v89
	ds_write_b32 v94, v92
	ds_write_b32 v95, v93
	ds_write_b32 v98, v96
	ds_write_b32 v99, v97
	ds_write_b32 v102, v100
	ds_write_b32 v103, v101
	s_cbranch_scc1 .LBB0_205
	s_waitcnt lgkmcnt(0)
	s_mul_i32 s7, s9, 0x600000
	s_mul_hi_u32 s6, s9, 0x600000
	s_add_u32 s7, s3, s7
	ds_read2_b32 v[18:19], v7 offset1:33
	s_addc_u32 s9, s10, s6
	s_and_b32 s6, 0xffff, s8
	s_waitcnt lgkmcnt(0)
	v_cvt_pk_bf16_f32 v18, v18, v19
	ds_read2_b32 v[20:21], v7 offset0:66 offset1:99
	s_bitset1_b32 s21, 11
	s_lshl_b32 s6, s6, 1
	s_waitcnt lgkmcnt(0)
	v_cvt_pk_bf16_f32 v19, v20, v21
	ds_read2_b32 v[20:21], v7 offset0:132 offset1:165
	s_add_u32 s6, s7, s6
	s_waitcnt lgkmcnt(0)
	v_cvt_pk_bf16_f32 v20, v20, v21
	ds_read2_b32 v[22:23], v7 offset0:198 offset1:231
	s_addc_u32 s7, s9, 0
	v_lshlrev_b32_e32 v16, 1, v10
	v_mov_b32_e32 v17, v4
	s_waitcnt lgkmcnt(0)
	v_cvt_pk_bf16_f32 v21, v22, v23
	v_or_b32_e32 v22, s21, v5
	v_lshl_add_u64 v[16:17], s[6:7], 0, v[16:17]
	v_lshlrev_b32_e32 v22, 11, v22
	v_mov_b32_e32 v23, v4
	v_lshl_add_u64 v[22:23], v[16:17], 0, v[22:23]
	global_store_dwordx4 v[22:23], v[18:21], off nt
	ds_read2_b32 v[18:19], v7 offset0:8 offset1:41
	s_mov_b32 s51, 0x40c000
	s_waitcnt lgkmcnt(0)
	v_cvt_pk_bf16_f32 v18, v18, v19
	ds_read2_b32 v[20:21], v7 offset0:74 offset1:107
	s_waitcnt lgkmcnt(0)
	v_cvt_pk_bf16_f32 v19, v20, v21
	ds_read2_b32 v[20:21], v7 offset0:140 offset1:173
	s_waitcnt lgkmcnt(0)
	v_cvt_pk_bf16_f32 v20, v20, v21
	ds_read2_b32 v[22:23], v7 offset0:206 offset1:239
	s_waitcnt lgkmcnt(0)
	v_cvt_pk_bf16_f32 v21, v22, v23
	v_or_b32_e32 v22, s21, v9
	v_lshlrev_b32_e32 v22, 11, v22
	v_mov_b32_e32 v23, v4
	v_lshl_add_u64 v[22:23], v[16:17], 0, v[22:23]
	global_store_dwordx4 v[22:23], v[18:21], off nt
	ds_read2_b32 v[18:19], v7 offset0:16 offset1:49
	s_mov_b64 s[48:49], 0x7ffff
	s_waitcnt lgkmcnt(0)
	v_cvt_pk_bf16_f32 v18, v18, v19
	ds_read2_b32 v[20:21], v7 offset0:82 offset1:115
	s_waitcnt lgkmcnt(0)
	v_cvt_pk_bf16_f32 v19, v20, v21
	ds_read2_b32 v[20:21], v7 offset0:148 offset1:181
	s_waitcnt lgkmcnt(0)
	v_cvt_pk_bf16_f32 v20, v20, v21
	ds_read2_b32 v[22:23], v7 offset0:214 offset1:247
	s_waitcnt lgkmcnt(0)
	v_cvt_pk_bf16_f32 v21, v22, v23
	v_or_b32_e32 v22, s21, v11
	v_lshlrev_b32_e32 v22, 11, v22
	v_mov_b32_e32 v23, v4
	v_lshl_add_u64 v[22:23], v[16:17], 0, v[22:23]
	global_store_dwordx4 v[22:23], v[18:21], off nt
	ds_read2_b32 v[18:19], v7 offset0:24 offset1:57
	s_waitcnt lgkmcnt(0)
	v_cvt_pk_bf16_f32 v18, v18, v19
	ds_read2_b32 v[20:21], v7 offset0:90 offset1:123
	s_waitcnt lgkmcnt(0)
	v_cvt_pk_bf16_f32 v19, v20, v21
	ds_read2_b32 v[20:21], v7 offset0:156 offset1:189
	s_waitcnt lgkmcnt(0)
	v_cvt_pk_bf16_f32 v20, v20, v21
	ds_read2_b32 v[22:23], v7 offset0:222 offset1:255
	s_waitcnt lgkmcnt(0)
	v_cvt_pk_bf16_f32 v21, v22, v23
	v_or_b32_e32 v22, s21, v32
	v_lshlrev_b32_e32 v22, 11, v22
	v_mov_b32_e32 v23, v4
	v_lshl_add_u64 v[16:17], v[16:17], 0, v[22:23]
	global_store_dwordx4 v[16:17], v[18:21], off nt
	s_waitcnt lgkmcnt(0)

.LBB0_208:
	s_andn2_b64 vcc, exec, s[6:7]
	s_cbranch_vccnz .LBB0_210
	s_add_i32 s6, s1, 0xffffae00
	s_lshr_b32 s6, s6, 9
	v_readlane_b32 s48, v253, 15
	s_mul_i32 s8, s6, 0xc00000
	v_readlane_b32 s58, v253, 25
	s_mul_hi_u32 s7, s6, 0xc00000
	v_readlane_b32 s59, v253, 26
	s_add_u32 s22, s58, s8
	s_addc_u32 s23, s59, s7
	s_mul_hi_u32 s8, s6, 0x600000
	s_mul_i32 s6, s6, 0x600000
	s_add_u32 s7, s3, s6
	s_addc_u32 s8, s10, s8
	s_bfe_u32 s9, s1, 0x40001
	s_mul_i32 s21, s9, 0xc0
	s_lshl_b32 s9, s1, 1
	s_and_b32 s9, s9, 0x3c0
	s_and_b32 s6, s1, 31
	v_or_b32_e32 v16, s9, v35
	s_lshl_b32 s6, s6, 6
	v_mul_u32_u24_e32 v16, 0xc00, v16
	v_and_or_b32 v18, s6, 64, v34
	v_lshlrev_b32_e32 v16, 2, v16
	v_mov_b32_e32 v17, v4
	v_lshl_add_u64 v[16:17], s[22:23], 0, v[16:17]
	v_add_lshl_u32 v18, v18, s21, 2
	v_mov_b32_e32 v19, v4
	s_waitcnt vmcnt(10)
	v_lshl_add_u64 v[108:109], v[16:17], 0, v[18:19]
	s_movk_i32 s21, 0x3000
	v_add_co_u32_e32 v20, vcc, s21, v108
	s_movk_i32 s21, 0x6000
	s_nop 0
	v_addc_co_u32_e32 v21, vcc, 0, v109, vcc
	v_add_co_u32_e32 v24, vcc, s21, v108
	s_mov_b32 s21, 0x9000
	s_nop 0
	v_addc_co_u32_e32 v25, vcc, 0, v109, vcc
	v_add_co_u32_e32 v28, vcc, s21, v108
	s_mov_b32 s21, 0xc000
	s_nop 0
	v_addc_co_u32_e32 v29, vcc, 0, v109, vcc
	v_add_co_u32_e32 v68, vcc, s21, v108
	s_mov_b32 s21, 0xf000
	s_nop 0
	v_addc_co_u32_e32 v69, vcc, 0, v109, vcc
	s_waitcnt vmcnt(1)
	v_add_co_u32_e32 v72, vcc, s21, v108
	s_mov_b32 s21, 0x12000
	s_nop 0
	v_addc_co_u32_e32 v73, vcc, 0, v109, vcc
	v_add_co_u32_e32 v76, vcc, s21, v108
	s_mov_b32 s21, 0x15000
	s_nop 0
	v_addc_co_u32_e32 v77, vcc, 0, v109, vcc
	v_add_co_u32_e32 v80, vcc, s21, v108
	s_mov_b32 s21, 0x18000
	s_nop 0
	v_addc_co_u32_e32 v81, vcc, 0, v109, vcc
	v_add_co_u32_e32 v84, vcc, s21, v108
	s_mov_b32 s21, 0x1b000
	s_nop 0
	v_addc_co_u32_e32 v85, vcc, 0, v109, vcc
	v_add_co_u32_e32 v88, vcc, s21, v108
	s_mov_b32 s21, 0x1e000
	s_nop 0
	v_addc_co_u32_e32 v89, vcc, 0, v109, vcc
	v_add_co_u32_e32 v92, vcc, s21, v108
	s_mov_b32 s21, 0x21000
	s_nop 0
	v_addc_co_u32_e32 v93, vcc, 0, v109, vcc
	v_add_co_u32_e32 v96, vcc, s21, v108
	s_mov_b32 s21, 0x24000
	s_nop 0
	v_addc_co_u32_e32 v97, vcc, 0, v109, vcc
	v_add_co_u32_e32 v100, vcc, s21, v108
	s_mov_b32 s21, 0x27000
	s_nop 0
	v_addc_co_u32_e32 v101, vcc, 0, v109, vcc
	v_add_co_u32_e32 v104, vcc, s21, v108
	s_mov_b32 s21, 0x2a000
	s_nop 0
	v_addc_co_u32_e32 v105, vcc, 0, v109, vcc
	v_add_co_u32_e32 v110, vcc, s21, v108
	s_mov_b32 s21, 0x2d000
	s_nop 0
	v_addc_co_u32_e32 v111, vcc, 0, v109, vcc
	v_add_co_u32_e32 v112, vcc, s21, v108
	global_load_dwordx4 v[16:19], v[108:109], off nt
	s_nop 0
	global_load_dwordx4 v[20:23], v[20:21], off nt
	s_nop 0
	global_load_dwordx4 v[24:27], v[24:25], off nt
	s_nop 0
	global_load_dwordx4 v[28:31], v[28:29], off nt
	s_nop 0
	global_load_dwordx4 v[68:71], v[68:69], off nt
	s_nop 0
	global_load_dwordx4 v[72:75], v[72:73], off nt
	s_nop 0
	global_load_dwordx4 v[76:79], v[76:77], off nt
	s_nop 0
	global_load_dwordx4 v[80:83], v[80:81], off nt
	v_addc_co_u32_e32 v113, vcc, 0, v109, vcc
	global_load_dwordx4 v[84:87], v[84:85], off nt
	s_nop 0
	global_load_dwordx4 v[88:91], v[88:89], off nt
	s_nop 0
	global_load_dwordx4 v[92:95], v[92:93], off nt
	s_nop 0
	global_load_dwordx4 v[96:99], v[96:97], off nt
	s_nop 0
	global_load_dwordx4 v[100:103], v[100:101], off nt
	s_nop 0
	global_load_dwordx4 v[104:107], v[104:105], off nt
	s_nop 0
	global_load_dwordx4 v[108:111], v[110:111], off nt
	s_nop 0
	global_load_dwordx4 v[112:115], v[112:113], off nt
	s_waitcnt vmcnt(14)
	v_cvt_pk_bf16_f32 v116, v16, v20
	s_waitcnt vmcnt(12)
	v_cvt_pk_bf16_f32 v117, v24, v28
	s_waitcnt vmcnt(10)
	v_cvt_pk_bf16_f32 v118, v68, v72
	s_waitcnt vmcnt(8)
	v_cvt_pk_bf16_f32 v119, v76, v80
	v_add_u32_e32 v24, v38, v36
	v_add_u32_e32 v28, v38, v37
	s_waitcnt vmcnt(6)
	v_cvt_pk_bf16_f32 v120, v84, v88
	s_waitcnt vmcnt(4)
	v_cvt_pk_bf16_f32 v121, v92, v96
	s_waitcnt vmcnt(2)
	v_cvt_pk_bf16_f32 v122, v100, v104
	s_waitcnt vmcnt(0)
	v_cvt_pk_bf16_f32 v123, v108, v112
	ds_write_b128 v24, v[116:119]
	ds_write_b128 v28, v[120:123]
	v_cvt_pk_bf16_f32 v116, v17, v21
	v_cvt_pk_bf16_f32 v117, v25, v29
	v_cvt_pk_bf16_f32 v118, v69, v73
	v_cvt_pk_bf16_f32 v119, v77, v81
	v_cvt_pk_bf16_f32 v120, v85, v89
	v_cvt_pk_bf16_f32 v121, v93, v97
	v_cvt_pk_bf16_f32 v122, v101, v105
	v_cvt_pk_bf16_f32 v123, v109, v113
	ds_write_b128 v24, v[116:119] offset:128
	ds_write_b128 v28, v[120:123] offset:128
	v_cvt_pk_bf16_f32 v116, v18, v22
	v_cvt_pk_bf16_f32 v117, v26, v30
	v_cvt_pk_bf16_f32 v118, v70, v74
	v_cvt_pk_bf16_f32 v119, v78, v82
	v_cvt_pk_bf16_f32 v120, v86, v90
	v_cvt_pk_bf16_f32 v121, v94, v98
	v_cvt_pk_bf16_f32 v122, v102, v106
	v_cvt_pk_bf16_f32 v123, v110, v114
	ds_write_b128 v24, v[116:119] offset:256
	ds_write_b128 v28, v[120:123] offset:256
	v_cvt_pk_bf16_f32 v16, v19, v23
	v_cvt_pk_bf16_f32 v17, v27, v31
	v_cvt_pk_bf16_f32 v18, v71, v75
	v_cvt_pk_bf16_f32 v19, v79, v83
	s_lshl_b32 s9, s9, 1
	v_cvt_pk_bf16_f32 v20, v87, v91
	v_cvt_pk_bf16_f32 v21, v95, v99
	v_cvt_pk_bf16_f32 v22, v103, v107
	v_cvt_pk_bf16_f32 v23, v111, v115
	ds_write_b128 v24, v[16:19] offset:384
	ds_write_b128 v28, v[20:23] offset:384
	s_add_u32 s22, s7, s9
	s_waitcnt lgkmcnt(0)
	s_addc_u32 s23, s8, 0
	v_lshlrev_b32_e32 v16, 1, v10
	v_mov_b32_e32 v17, v4
	v_lshl_add_u64 v[24:25], s[22:23], 0, v[16:17]
	v_add_u32_e32 v16, v39, v40
	ds_read_b128 v[16:19], v16
	v_or_b32_e32 v20, s6, v5
	v_lshlrev_b32_e32 v20, 11, v20
	v_mov_b32_e32 v21, v4
	v_lshl_add_u64 v[26:27], v[24:25], 0, v[20:21]
	v_add_u32_e32 v20, v41, v42
	ds_read_b128 v[20:23], v20
	s_waitcnt lgkmcnt(1)
	global_store_dwordx4 v[26:27], v[16:19], off nt
	v_readlane_b32 s49, v253, 16
	v_readlane_b32 s51, v253, 18
	v_or_b32_e32 v16, s6, v9
	v_lshlrev_b32_e32 v16, 11, v16
	v_mov_b32_e32 v17, v4
	v_lshl_add_u64 v[16:17], v[24:25], 0, v[16:17]
	s_waitcnt lgkmcnt(0)
	global_store_dwordx4 v[16:17], v[20:23], off nt
	v_add_u32_e32 v16, v43, v44
	ds_read_b128 v[16:19], v16
	v_or_b32_e32 v20, s6, v11
	v_lshlrev_b32_e32 v20, 11, v20
	v_mov_b32_e32 v21, v4
	v_lshl_add_u64 v[26:27], v[24:25], 0, v[20:21]
	v_add_u32_e32 v20, v45, v46
	ds_read_b128 v[20:23], v20
	s_waitcnt lgkmcnt(1)
	global_store_dwordx4 v[26:27], v[16:19], off nt
	s_mov_b64 s[48:49], 0x7ffff
	s_mov_b32 s51, 0x40c000
	v_or_b32_e32 v16, s6, v32
	v_lshlrev_b32_e32 v16, 11, v16
	v_mov_b32_e32 v17, v4
	v_lshl_add_u64 v[16:17], v[24:25], 0, v[16:17]
	s_waitcnt lgkmcnt(0)
	global_store_dwordx4 v[16:17], v[20:23], off nt
	v_add_u32_e32 v16, v48, v40
	ds_read_b128 v[16:19], v16
	v_or_b32_e32 v20, s6, v47
	v_lshlrev_b32_e32 v20, 11, v20
	v_mov_b32_e32 v21, v4
	v_lshl_add_u64 v[26:27], v[24:25], 0, v[20:21]
	v_add_u32_e32 v20, v50, v51
	ds_read_b128 v[20:23], v20
	s_waitcnt lgkmcnt(1)
	global_store_dwordx4 v[26:27], v[16:19], off nt
	v_readlane_b32 s50, v253, 17
	v_readlane_b32 s52, v253, 19
	v_or_b32_e32 v16, s6, v49
	v_lshlrev_b32_e32 v16, 11, v16
	v_mov_b32_e32 v17, v4
	v_lshl_add_u64 v[16:17], v[24:25], 0, v[16:17]
	s_waitcnt lgkmcnt(0)
	global_store_dwordx4 v[16:17], v[20:23], off nt
	v_add_u32_e32 v16, v53, v54
	ds_read_b128 v[16:19], v16
	v_or_b32_e32 v20, s6, v52
	v_lshlrev_b32_e32 v20, 11, v20
	v_mov_b32_e32 v21, v4
	v_lshl_add_u64 v[26:27], v[24:25], 0, v[20:21]
	v_add_u32_e32 v20, v56, v57
	ds_read_b128 v[20:23], v20
	s_waitcnt lgkmcnt(1)
	global_store_dwordx4 v[26:27], v[16:19], off nt
	v_readlane_b32 s53, v253, 20
	v_readlane_b32 s54, v253, 21
	v_or_b32_e32 v16, s6, v55
	v_lshlrev_b32_e32 v16, 11, v16
	v_mov_b32_e32 v17, v4
	v_lshl_add_u64 v[16:17], v[24:25], 0, v[16:17]
	s_waitcnt lgkmcnt(0)
	global_store_dwordx4 v[16:17], v[20:23], off nt
	s_waitcnt lgkmcnt(0)
	v_readlane_b32 s55, v253, 22
	v_readlane_b32 s56, v253, 23
	v_readlane_b32 s57, v253, 24
	v_readlane_b32 s60, v253, 27
	v_readlane_b32 s61, v253, 28
	v_readlane_b32 s62, v253, 29
	v_readlane_b32 s63, v253, 30

.LBB0_211:
	s_andn2_b64 vcc, exec, s[6:7]
	s_cbranch_vccnz .LBB0_213
	s_add_i32 s6, s1, 0xffffb200
	v_readlane_b32 s8, v254, 28
	v_readlane_b32 s9, v254, 29
	s_lshr_b32 s8, s6, 9
	v_readlane_b32 s24, v253, 0
	s_lshl_b64 s[6:7], s[8:9], 23
	v_readlane_b32 s28, v253, 4
	v_readlane_b32 s29, v253, 5
	s_add_u32 s22, s28, s6
	s_addc_u32 s23, s29, s7
	s_mov_b32 s7, s9
	v_writelane_b32 v254, s6, 28
	s_lshl_b64 s[8:9], s[8:9], 22
	v_mov_b32_e32 v17, v4
	v_writelane_b32 v254, s7, 29
	s_add_u32 s7, s11, s8
	s_addc_u32 s8, s15, s9
	s_lshl_b32 s6, s1, 6
	s_and_b32 s9, s1, 0x1c0
	s_and_b32 s6, s6, 0xfc0
	v_or_b32_e32 v16, s9, v35
	v_or_b32_e32 v18, s6, v34
	v_lshlrev_b32_e32 v16, 14, v16
	v_lshl_add_u64 v[16:17], s[22:23], 0, v[16:17]
	v_lshlrev_b32_e32 v18, 2, v18
	v_mov_b32_e32 v19, v4
	s_waitcnt vmcnt(10)
	v_lshl_add_u64 v[108:109], v[16:17], 0, v[18:19]
	s_movk_i32 s21, 0x4000
	v_add_co_u32_e32 v20, vcc, s21, v108
	s_mov_b32 s21, 0x8000
	s_nop 0
	v_addc_co_u32_e32 v21, vcc, 0, v109, vcc
	v_add_co_u32_e32 v24, vcc, s21, v108
	s_mov_b32 s21, 0xc000
	s_nop 0
	v_addc_co_u32_e32 v25, vcc, 0, v109, vcc
	v_add_co_u32_e32 v28, vcc, s21, v108
	s_mov_b32 s21, 0x14000
	s_nop 0
	v_addc_co_u32_e32 v29, vcc, 0, v109, vcc
	v_add_co_u32_e32 v68, vcc, s91, v108
	global_load_dwordx4 v[16:19], v[108:109], off nt
	s_nop 0
	global_load_dwordx4 v[20:23], v[20:21], off nt
	v_addc_co_u32_e32 v69, vcc, 0, v109, vcc
	s_waitcnt vmcnt(3)
	v_add_co_u32_e32 v72, vcc, s21, v108
	s_mov_b32 s21, 0x18000
	s_nop 0
	v_addc_co_u32_e32 v73, vcc, 0, v109, vcc
	v_add_co_u32_e32 v76, vcc, s21, v108
	s_mov_b32 s21, 0x1c000
	s_nop 0
	v_addc_co_u32_e32 v77, vcc, 0, v109, vcc
	v_add_co_u32_e32 v80, vcc, s21, v108
	s_mov_b32 s21, 0x24000
	s_nop 0
	v_addc_co_u32_e32 v81, vcc, 0, v109, vcc
	v_add_co_u32_e32 v84, vcc, s94, v108
	global_load_dwordx4 v[24:27], v[24:25], off nt
	s_nop 0
	global_load_dwordx4 v[28:31], v[28:29], off nt
	v_addc_co_u32_e32 v85, vcc, 0, v109, vcc
	v_add_co_u32_e32 v88, vcc, s21, v108
	s_mov_b32 s21, 0x28000
	s_nop 0
	v_addc_co_u32_e32 v89, vcc, 0, v109, vcc
	v_add_co_u32_e32 v92, vcc, s21, v108
	s_mov_b32 s21, 0x2c000
	s_nop 0
	v_addc_co_u32_e32 v93, vcc, 0, v109, vcc
	v_add_co_u32_e32 v96, vcc, s21, v108
	s_mov_b32 s21, 0x30000
	s_nop 0
	v_addc_co_u32_e32 v97, vcc, 0, v109, vcc
	v_add_co_u32_e32 v100, vcc, s21, v108
	s_mov_b32 s21, 0x34000
	s_nop 0
	v_addc_co_u32_e32 v101, vcc, 0, v109, vcc
	v_add_co_u32_e32 v104, vcc, s21, v108
	s_mov_b32 s21, 0x38000
	s_nop 0
	v_addc_co_u32_e32 v105, vcc, 0, v109, vcc
	v_add_co_u32_e32 v110, vcc, s21, v108
	s_mov_b32 s21, 0x3c000
	s_nop 0
	v_addc_co_u32_e32 v111, vcc, 0, v109, vcc
	v_add_co_u32_e32 v112, vcc, s21, v108
	global_load_dwordx4 v[68:71], v[68:69], off nt
	s_nop 0
	global_load_dwordx4 v[72:75], v[72:73], off nt
	s_nop 0
	global_load_dwordx4 v[76:79], v[76:77], off nt
	s_nop 0
	global_load_dwordx4 v[80:83], v[80:81], off nt
	v_addc_co_u32_e32 v113, vcc, 0, v109, vcc
	global_load_dwordx4 v[84:87], v[84:85], off nt
	s_nop 0
	global_load_dwordx4 v[88:91], v[88:89], off nt
	s_nop 0
	global_load_dwordx4 v[92:95], v[92:93], off nt
	s_nop 0
	global_load_dwordx4 v[96:99], v[96:97], off nt
	s_nop 0
	global_load_dwordx4 v[100:103], v[100:101], off nt
	s_nop 0
	global_load_dwordx4 v[104:107], v[104:105], off nt
	s_nop 0
	global_load_dwordx4 v[108:111], v[110:111], off nt
	s_nop 0
	global_load_dwordx4 v[112:115], v[112:113], off nt
	s_waitcnt vmcnt(14)
	v_cvt_pk_bf16_f32 v116, v16, v20
	s_waitcnt vmcnt(12)
	v_cvt_pk_bf16_f32 v117, v24, v28
	s_waitcnt vmcnt(10)
	v_cvt_pk_bf16_f32 v118, v68, v72
	s_waitcnt vmcnt(8)
	v_cvt_pk_bf16_f32 v119, v76, v80
	v_add_u32_e32 v24, v38, v36
	v_add_u32_e32 v28, v38, v37
	s_waitcnt vmcnt(6)
	v_cvt_pk_bf16_f32 v120, v84, v88
	s_waitcnt vmcnt(4)
	v_cvt_pk_bf16_f32 v121, v92, v96
	s_waitcnt vmcnt(2)
	v_cvt_pk_bf16_f32 v122, v100, v104
	s_waitcnt vmcnt(0)
	v_cvt_pk_bf16_f32 v123, v108, v112
	ds_write_b128 v24, v[116:119]
	ds_write_b128 v28, v[120:123]
	v_cvt_pk_bf16_f32 v116, v17, v21
	v_cvt_pk_bf16_f32 v117, v25, v29
	v_cvt_pk_bf16_f32 v118, v69, v73
	v_cvt_pk_bf16_f32 v119, v77, v81
	v_cvt_pk_bf16_f32 v120, v85, v89
	v_cvt_pk_bf16_f32 v121, v93, v97
	v_cvt_pk_bf16_f32 v122, v101, v105
	v_cvt_pk_bf16_f32 v123, v109, v113
	ds_write_b128 v24, v[116:119] offset:128
	ds_write_b128 v28, v[120:123] offset:128
	v_cvt_pk_bf16_f32 v116, v18, v22
	v_cvt_pk_bf16_f32 v117, v26, v30
	v_cvt_pk_bf16_f32 v118, v70, v74
	v_cvt_pk_bf16_f32 v119, v78, v82
	v_cvt_pk_bf16_f32 v120, v86, v90
	v_cvt_pk_bf16_f32 v121, v94, v98
	v_cvt_pk_bf16_f32 v122, v102, v106
	v_cvt_pk_bf16_f32 v123, v110, v114
	ds_write_b128 v24, v[116:119] offset:256
	ds_write_b128 v28, v[120:123] offset:256
	v_cvt_pk_bf16_f32 v16, v19, v23
	v_cvt_pk_bf16_f32 v17, v27, v31
	v_cvt_pk_bf16_f32 v18, v71, v75
	v_cvt_pk_bf16_f32 v19, v79, v83
	s_lshl_b32 s9, s9, 1
	v_cvt_pk_bf16_f32 v20, v87, v91
	v_cvt_pk_bf16_f32 v21, v95, v99
	v_cvt_pk_bf16_f32 v22, v103, v107
	v_cvt_pk_bf16_f32 v23, v111, v115
	ds_write_b128 v24, v[16:19] offset:384
	ds_write_b128 v28, v[20:23] offset:384
	s_add_u32 s22, s7, s9
	s_waitcnt lgkmcnt(0)
	s_addc_u32 s23, s8, 0
	v_lshlrev_b32_e32 v16, 1, v10
	v_mov_b32_e32 v17, v4
	v_lshl_add_u64 v[24:25], s[22:23], 0, v[16:17]
	v_add_u32_e32 v16, v39, v40
	ds_read_b128 v[16:19], v16
	v_or_b32_e32 v20, s6, v5
	v_lshlrev_b32_e32 v20, 10, v20
	v_mov_b32_e32 v21, v4
	v_lshl_add_u64 v[26:27], v[24:25], 0, v[20:21]
	v_add_u32_e32 v20, v41, v42
	ds_read_b128 v[20:23], v20
	s_waitcnt lgkmcnt(1)
	global_store_dwordx4 v[26:27], v[16:19], off nt
	v_readlane_b32 s25, v253, 1
	v_readlane_b32 s26, v253, 2
	v_or_b32_e32 v16, s6, v9
	v_lshlrev_b32_e32 v16, 10, v16
	v_mov_b32_e32 v17, v4
	v_lshl_add_u64 v[16:17], v[24:25], 0, v[16:17]
	s_waitcnt lgkmcnt(0)
	global_store_dwordx4 v[16:17], v[20:23], off nt
	v_add_u32_e32 v16, v43, v44
	ds_read_b128 v[16:19], v16
	v_or_b32_e32 v20, s6, v11
	v_lshlrev_b32_e32 v20, 10, v20
	v_mov_b32_e32 v21, v4
	v_lshl_add_u64 v[26:27], v[24:25], 0, v[20:21]
	v_add_u32_e32 v20, v45, v46
	ds_read_b128 v[20:23], v20
	s_waitcnt lgkmcnt(1)
	global_store_dwordx4 v[26:27], v[16:19], off nt
	v_readlane_b32 s27, v253, 3
	v_readlane_b32 s30, v253, 6
	v_or_b32_e32 v16, s6, v32
	v_lshlrev_b32_e32 v16, 10, v16
	v_mov_b32_e32 v17, v4
	v_lshl_add_u64 v[16:17], v[24:25], 0, v[16:17]
	s_waitcnt lgkmcnt(0)
	global_store_dwordx4 v[16:17], v[20:23], off nt
	v_add_u32_e32 v16, v48, v40
	ds_read_b128 v[16:19], v16
	v_or_b32_e32 v20, s6, v47
	v_lshlrev_b32_e32 v20, 10, v20
	v_mov_b32_e32 v21, v4
	v_lshl_add_u64 v[26:27], v[24:25], 0, v[20:21]
	v_add_u32_e32 v20, v50, v51
	ds_read_b128 v[20:23], v20
	s_waitcnt lgkmcnt(1)
	global_store_dwordx4 v[26:27], v[16:19], off nt
	v_readlane_b32 s31, v253, 7
	s_nop 0
	v_or_b32_e32 v16, s6, v49
	v_lshlrev_b32_e32 v16, 10, v16
	v_mov_b32_e32 v17, v4
	v_lshl_add_u64 v[16:17], v[24:25], 0, v[16:17]
	s_waitcnt lgkmcnt(0)
	global_store_dwordx4 v[16:17], v[20:23], off nt
	v_add_u32_e32 v16, v53, v54
	ds_read_b128 v[16:19], v16
	v_or_b32_e32 v20, s6, v52
	v_lshlrev_b32_e32 v20, 10, v20
	v_mov_b32_e32 v21, v4
	v_lshl_add_u64 v[26:27], v[24:25], 0, v[20:21]
	v_add_u32_e32 v20, v56, v57
	ds_read_b128 v[20:23], v20
	s_waitcnt lgkmcnt(1)
	global_store_dwordx4 v[26:27], v[16:19], off nt
	s_nop 1
	v_or_b32_e32 v16, s6, v55
	v_lshlrev_b32_e32 v16, 10, v16
	v_mov_b32_e32 v17, v4
	v_lshl_add_u64 v[16:17], v[24:25], 0, v[16:17]
	s_waitcnt lgkmcnt(0)
	global_store_dwordx4 v[16:17], v[20:23], off nt
	s_waitcnt lgkmcnt(0)

.LBB0_214:
	s_andn2_b64 vcc, exec, s[6:7]
	s_cbranch_vccnz .LBB0_216
	v_readlane_b32 s6, v254, 28
	s_add_i32 s21, s1, 0xffffd200
	v_readlane_b32 s7, v254, 29
	s_mov_b32 s9, s7
	s_lshr_b32 s8, s21, 12
	s_lshl_b64 s[6:7], s[8:9], 26
	s_add_u32 s22, s80, s6
	s_addc_u32 s23, s81, s7
	s_mov_b32 s7, s9
	v_writelane_b32 v254, s6, 28
	s_lshl_b64 s[8:9], s[8:9], 25
	v_mov_b32_e32 v17, v4
	v_writelane_b32 v254, s7, 29
	s_add_u32 s7, s19, s8
	s_addc_u32 s8, s20, s9
	s_lshl_b32 s6, s1, 6
	s_and_b32 s9, s21, 0xfc0
	s_and_b32 s6, s6, 0xfc0
	v_or_b32_e32 v16, s9, v35
	v_or_b32_e32 v18, s6, v34
	v_lshlrev_b32_e32 v16, 14, v16
	v_lshl_add_u64 v[16:17], s[22:23], 0, v[16:17]
	v_lshlrev_b32_e32 v18, 2, v18
	v_mov_b32_e32 v19, v4
	s_waitcnt vmcnt(10)
	v_lshl_add_u64 v[108:109], v[16:17], 0, v[18:19]
	s_movk_i32 s21, 0x4000
	v_add_co_u32_e32 v20, vcc, s21, v108
	s_mov_b32 s21, 0x8000
	s_nop 0
	v_addc_co_u32_e32 v21, vcc, 0, v109, vcc
	v_add_co_u32_e32 v24, vcc, s21, v108
	s_mov_b32 s21, 0xc000
	s_nop 0
	v_addc_co_u32_e32 v25, vcc, 0, v109, vcc
	v_add_co_u32_e32 v28, vcc, s21, v108
	s_mov_b32 s21, 0x14000
	s_nop 0
	v_addc_co_u32_e32 v29, vcc, 0, v109, vcc
	v_add_co_u32_e32 v68, vcc, s91, v108
	global_load_dwordx4 v[16:19], v[108:109], off nt
	s_nop 0
	global_load_dwordx4 v[20:23], v[20:21], off nt
	v_addc_co_u32_e32 v69, vcc, 0, v109, vcc
	s_waitcnt vmcnt(3)
	v_add_co_u32_e32 v72, vcc, s21, v108
	s_mov_b32 s21, 0x18000
	s_nop 0
	v_addc_co_u32_e32 v73, vcc, 0, v109, vcc
	v_add_co_u32_e32 v76, vcc, s21, v108
	s_mov_b32 s21, 0x1c000
	s_nop 0
	v_addc_co_u32_e32 v77, vcc, 0, v109, vcc
	v_add_co_u32_e32 v80, vcc, s21, v108
	s_mov_b32 s21, 0x24000
	s_nop 0
	v_addc_co_u32_e32 v81, vcc, 0, v109, vcc
	v_add_co_u32_e32 v84, vcc, s94, v108
	global_load_dwordx4 v[24:27], v[24:25], off nt
	s_nop 0
	global_load_dwordx4 v[28:31], v[28:29], off nt
	v_addc_co_u32_e32 v85, vcc, 0, v109, vcc
	v_add_co_u32_e32 v88, vcc, s21, v108
	s_mov_b32 s21, 0x28000
	s_nop 0
	v_addc_co_u32_e32 v89, vcc, 0, v109, vcc
	v_add_co_u32_e32 v92, vcc, s21, v108
	s_mov_b32 s21, 0x2c000
	s_nop 0
	v_addc_co_u32_e32 v93, vcc, 0, v109, vcc
	v_add_co_u32_e32 v96, vcc, s21, v108
	s_mov_b32 s21, 0x30000
	s_nop 0
	v_addc_co_u32_e32 v97, vcc, 0, v109, vcc
	v_add_co_u32_e32 v100, vcc, s21, v108
	s_mov_b32 s21, 0x34000
	s_nop 0
	v_addc_co_u32_e32 v101, vcc, 0, v109, vcc
	v_add_co_u32_e32 v104, vcc, s21, v108
	s_mov_b32 s21, 0x38000
	s_nop 0
	v_addc_co_u32_e32 v105, vcc, 0, v109, vcc
	v_add_co_u32_e32 v110, vcc, s21, v108
	s_mov_b32 s21, 0x3c000
	s_nop 0
	v_addc_co_u32_e32 v111, vcc, 0, v109, vcc
	v_add_co_u32_e32 v112, vcc, s21, v108
	global_load_dwordx4 v[68:71], v[68:69], off nt
	s_nop 0
	global_load_dwordx4 v[72:75], v[72:73], off nt
	s_nop 0
	global_load_dwordx4 v[76:79], v[76:77], off nt
	s_nop 0
	global_load_dwordx4 v[80:83], v[80:81], off nt
	v_addc_co_u32_e32 v113, vcc, 0, v109, vcc
	global_load_dwordx4 v[84:87], v[84:85], off nt
	s_nop 0
	global_load_dwordx4 v[88:91], v[88:89], off nt
	s_nop 0
	global_load_dwordx4 v[92:95], v[92:93], off nt
	s_nop 0
	global_load_dwordx4 v[96:99], v[96:97], off nt
	s_nop 0
	global_load_dwordx4 v[100:103], v[100:101], off nt
	s_nop 0
	global_load_dwordx4 v[104:107], v[104:105], off nt
	s_nop 0
	global_load_dwordx4 v[108:111], v[110:111], off nt
	s_nop 0
	global_load_dwordx4 v[112:115], v[112:113], off nt
	s_waitcnt vmcnt(14)
	v_cvt_pk_bf16_f32 v116, v16, v20
	s_waitcnt vmcnt(12)
	v_cvt_pk_bf16_f32 v117, v24, v28
	s_waitcnt vmcnt(10)
	v_cvt_pk_bf16_f32 v118, v68, v72
	s_waitcnt vmcnt(8)
	v_cvt_pk_bf16_f32 v119, v76, v80
	v_add_u32_e32 v24, v38, v36
	v_add_u32_e32 v28, v38, v37
	s_waitcnt vmcnt(6)
	v_cvt_pk_bf16_f32 v120, v84, v88
	s_waitcnt vmcnt(4)
	v_cvt_pk_bf16_f32 v121, v92, v96
	s_waitcnt vmcnt(2)
	v_cvt_pk_bf16_f32 v122, v100, v104
	s_waitcnt vmcnt(0)
	v_cvt_pk_bf16_f32 v123, v108, v112
	ds_write_b128 v24, v[116:119]
	ds_write_b128 v28, v[120:123]
	v_cvt_pk_bf16_f32 v116, v17, v21
	v_cvt_pk_bf16_f32 v117, v25, v29
	v_cvt_pk_bf16_f32 v118, v69, v73
	v_cvt_pk_bf16_f32 v119, v77, v81
	v_cvt_pk_bf16_f32 v120, v85, v89
	v_cvt_pk_bf16_f32 v121, v93, v97
	v_cvt_pk_bf16_f32 v122, v101, v105
	v_cvt_pk_bf16_f32 v123, v109, v113
	ds_write_b128 v24, v[116:119] offset:128
	ds_write_b128 v28, v[120:123] offset:128
	v_cvt_pk_bf16_f32 v116, v18, v22
	v_cvt_pk_bf16_f32 v117, v26, v30
	v_cvt_pk_bf16_f32 v118, v70, v74
	v_cvt_pk_bf16_f32 v119, v78, v82
	v_cvt_pk_bf16_f32 v120, v86, v90
	v_cvt_pk_bf16_f32 v121, v94, v98
	v_cvt_pk_bf16_f32 v122, v102, v106
	v_cvt_pk_bf16_f32 v123, v110, v114
	ds_write_b128 v24, v[116:119] offset:256
	ds_write_b128 v28, v[120:123] offset:256
	v_cvt_pk_bf16_f32 v16, v19, v23
	v_cvt_pk_bf16_f32 v17, v27, v31
	v_cvt_pk_bf16_f32 v18, v71, v75
	v_cvt_pk_bf16_f32 v19, v79, v83
	s_lshl_b32 s9, s9, 1
	v_cvt_pk_bf16_f32 v20, v87, v91
	v_cvt_pk_bf16_f32 v21, v95, v99
	v_cvt_pk_bf16_f32 v22, v103, v107
	v_cvt_pk_bf16_f32 v23, v111, v115
	ds_write_b128 v24, v[16:19] offset:384
	ds_write_b128 v28, v[20:23] offset:384
	s_add_u32 s22, s7, s9
	s_waitcnt lgkmcnt(0)
	s_addc_u32 s23, s8, 0
	v_lshlrev_b32_e32 v16, 1, v10
	v_mov_b32_e32 v17, v4
	v_lshl_add_u64 v[24:25], s[22:23], 0, v[16:17]
	v_add_u32_e32 v16, v39, v40
	ds_read_b128 v[16:19], v16
	v_or_b32_e32 v20, s6, v5
	v_lshlrev_b32_e32 v20, 13, v20
	v_mov_b32_e32 v21, v4
	v_lshl_add_u64 v[26:27], v[24:25], 0, v[20:21]
	v_add_u32_e32 v20, v41, v42
	ds_read_b128 v[20:23], v20
	s_waitcnt lgkmcnt(1)
	global_store_dwordx4 v[26:27], v[16:19], off nt
	s_nop 1
	v_or_b32_e32 v16, s6, v9
	v_lshlrev_b32_e32 v16, 13, v16
	v_mov_b32_e32 v17, v4
	v_lshl_add_u64 v[16:17], v[24:25], 0, v[16:17]
	s_waitcnt lgkmcnt(0)
	global_store_dwordx4 v[16:17], v[20:23], off nt
	v_add_u32_e32 v16, v43, v44
	ds_read_b128 v[16:19], v16
	v_or_b32_e32 v20, s6, v11
	v_lshlrev_b32_e32 v20, 13, v20
	v_mov_b32_e32 v21, v4
	v_lshl_add_u64 v[26:27], v[24:25], 0, v[20:21]
	v_add_u32_e32 v20, v45, v46
	ds_read_b128 v[20:23], v20
	s_waitcnt lgkmcnt(1)
	global_store_dwordx4 v[26:27], v[16:19], off nt
	s_nop 1
	v_or_b32_e32 v16, s6, v32
	v_lshlrev_b32_e32 v16, 13, v16
	v_mov_b32_e32 v17, v4
	v_lshl_add_u64 v[16:17], v[24:25], 0, v[16:17]
	s_waitcnt lgkmcnt(0)
	global_store_dwordx4 v[16:17], v[20:23], off nt
	v_add_u32_e32 v16, v48, v40
	ds_read_b128 v[16:19], v16
	v_or_b32_e32 v20, s6, v47
	v_lshlrev_b32_e32 v20, 13, v20
	v_mov_b32_e32 v21, v4
	v_lshl_add_u64 v[26:27], v[24:25], 0, v[20:21]
	v_add_u32_e32 v20, v50, v51
	ds_read_b128 v[20:23], v20
	s_waitcnt lgkmcnt(1)
	global_store_dwordx4 v[26:27], v[16:19], off nt
	s_nop 1
	v_or_b32_e32 v16, s6, v49
	v_lshlrev_b32_e32 v16, 13, v16
	v_mov_b32_e32 v17, v4
	v_lshl_add_u64 v[16:17], v[24:25], 0, v[16:17]
	s_waitcnt lgkmcnt(0)
	global_store_dwordx4 v[16:17], v[20:23], off nt
	v_add_u32_e32 v16, v53, v54
	ds_read_b128 v[16:19], v16
	v_or_b32_e32 v20, s6, v52
	v_lshlrev_b32_e32 v20, 13, v20
	v_mov_b32_e32 v21, v4
	v_lshl_add_u64 v[26:27], v[24:25], 0, v[20:21]
	v_add_u32_e32 v20, v56, v57
	ds_read_b128 v[20:23], v20
	s_waitcnt lgkmcnt(1)
	global_store_dwordx4 v[26:27], v[16:19], off nt
	s_nop 1
	v_or_b32_e32 v16, s6, v55
	v_lshlrev_b32_e32 v16, 13, v16
	v_mov_b32_e32 v17, v4
	v_lshl_add_u64 v[16:17], v[24:25], 0, v[16:17]
	s_waitcnt lgkmcnt(0)
	global_store_dwordx4 v[16:17], v[20:23], off nt
	s_waitcnt lgkmcnt(0)

.LBB0_231:
	s_or_b64 exec, exec, s[42:43]
	s_waitcnt vmcnt(0)
	v_cvt_pk_bf16_f32 v34, v34, v35
	v_cvt_pk_bf16_f32 v35, v36, v37
	v_cvt_pk_bf16_f32 v36, v30, v31
	v_alignbit_b32 v1, v55, v54, 21
	v_mov_b64_e32 v[30:31], s[16:17]
	v_mad_u64_u32 v[30:31], s[2:3], v1, s19, v[30:31]
	v_cvt_pk_bf16_f32 v37, v32, v33
	v_mov_b32_e32 v32, v31
	v_lshrrev_b32_e32 v1, 21, v55
	v_mad_u64_u32 v[32:33], s[2:3], v1, s19, v[32:33]
	v_and_b32_e32 v1, 0xfffff8, v42
	v_mov_b32_e32 v31, v32
	v_lshlrev_b32_e32 v32, 1, v1
	v_mov_b32_e32 v33, v4
	v_lshl_add_u64 v[30:31], v[30:31], 0, v[32:33]
	v_add_co_u32_e32 v30, vcc, 0x20f40000, v30
	s_nop 1
	v_addc_co_u32_e32 v31, vcc, 0, v31, vcc
	global_store_dwordx4 v[30:31], v[34:37], off nt
	s_and_saveexec_b64 s[42:43], s[6:7]
	s_cbranch_execnz .LBB0_234
	s_or_b64 exec, exec, s[42:43]
	s_and_saveexec_b64 s[6:7], s[10:11]
	s_cbranch_execnz .LBB0_235

.LBB0_234:
	v_alignbit_b32 v1, v53, v52, 21
	v_mov_b64_e32 v[34:35], s[16:17]
	v_mad_u64_u32 v[34:35], s[2:3], v1, s19, v[34:35]
	v_mov_b32_e32 v36, v35
	v_lshrrev_b32_e32 v1, 21, v53
	v_mad_u64_u32 v[36:37], s[2:3], v1, s19, v[36:37]
	v_add_u32_e32 v1, s36, v42
	v_and_b32_e32 v1, 0xfffff8, v1
	v_mov_b32_e32 v35, v36
	v_lshlrev_b32_e32 v36, 1, v1
	v_mov_b32_e32 v37, v4
	v_lshl_add_u64 v[34:35], v[34:35], 0, v[36:37]
	v_add_co_u32_e32 v34, vcc, 0x20f40000, v34
	v_cvt_pk_bf16_f32 v30, v6, v7
	v_cvt_pk_bf16_f32 v31, v8, v9
	v_cvt_pk_bf16_f32 v32, v14, v15
	v_cvt_pk_bf16_f32 v33, v16, v17
	s_nop 1
	v_addc_co_u32_e32 v35, vcc, 0, v35, vcc
	global_store_dwordx4 v[34:35], v[30:33], off nt
	s_or_b64 exec, exec, s[42:43]
	s_and_saveexec_b64 s[6:7], s[10:11]
	s_cbranch_execz .LBB0_233
.LBB0_235:
	v_alignbit_b32 v1, v59, v58, 21
	v_mov_b64_e32 v[34:35], s[16:17]
	v_mad_u64_u32 v[34:35], s[2:3], v1, s19, v[34:35]
	v_mov_b32_e32 v36, v35
	v_lshrrev_b32_e32 v1, 21, v59
	v_mad_u64_u32 v[36:37], s[2:3], v1, s19, v[36:37]
	v_add_u32_e32 v1, s30, v42
	v_and_b32_e32 v1, 0xfffff8, v1
	v_mov_b32_e32 v35, v36
	v_lshlrev_b32_e32 v36, 1, v1
	v_mov_b32_e32 v37, v4
	v_lshl_add_u64 v[34:35], v[34:35], 0, v[36:37]
	v_add_co_u32_e32 v34, vcc, 0x20f40000, v34
	v_cvt_pk_bf16_f32 v30, v10, v11
	v_cvt_pk_bf16_f32 v31, v12, v13
	v_cvt_pk_bf16_f32 v32, v22, v23
	v_cvt_pk_bf16_f32 v33, v24, v25
	s_nop 1
	v_addc_co_u32_e32 v35, vcc, 0, v35, vcc
	global_store_dwordx4 v[34:35], v[30:33], off nt
	s_or_b64 exec, exec, s[6:7]
	s_and_saveexec_b64 s[6:7], s[8:9]
	s_cbranch_execz .LBB0_224
.LBB0_236:
	v_alignbit_b32 v1, v57, v56, 21
	v_mov_b64_e32 v[34:35], s[16:17]
	v_mad_u64_u32 v[34:35], s[2:3], v1, s19, v[34:35]
	v_mov_b32_e32 v36, v35
	v_lshrrev_b32_e32 v1, 21, v57
	v_mad_u64_u32 v[36:37], s[2:3], v1, s19, v[36:37]
	s_mul_i32 s2, s0, 0x3000
	s_nop 0
	v_add_u32_e32 v1, s2, v42
	v_and_b32_e32 v1, 0xfffff8, v1
	v_mov_b32_e32 v35, v36
	v_lshlrev_b32_e32 v36, 1, v1
	v_mov_b32_e32 v37, v4
	v_lshl_add_u64 v[34:35], v[34:35], 0, v[36:37]
	v_add_co_u32_e32 v34, vcc, 0x20f40000, v34
	v_cvt_pk_bf16_f32 v30, v18, v19
	v_cvt_pk_bf16_f32 v31, v20, v21
	v_cvt_pk_bf16_f32 v32, v26, v27
	v_cvt_pk_bf16_f32 v33, v28, v29
	s_nop 1
	v_addc_co_u32_e32 v35, vcc, 0, v35, vcc
	global_store_dwordx4 v[34:35], v[30:33], off nt
	s_branch .LBB0_224

.LBB0_239:
	v_alignbit_b32 v1, v39, v38, 18
	v_mov_b64_e32 v[8:9], s[8:9]
	v_mad_u64_u32 v[8:9], s[2:3], v1, s51, v[8:9]
	v_lshrrev_b32_e32 v1, 18, v39
	v_mad_u32_u24 v9, v1, s51, v9
	v_bfe_u32 v1, v38, 14, 4
	v_mul_u32_u24_e32 v1, 0x810, v1
	v_bfe_u32 v5, v38, 3, 11
	v_add_lshl_u32 v10, v1, v5, 7
	v_mov_b32_e32 v11, v4
	v_and_b32_e32 v1, 56, v2
	v_lshl_add_u64 v[8:9], v[8:9], 0, v[10:11]
	v_lshlrev_b32_e32 v10, 1, v1
	v_lshl_add_u64 v[16:17], v[8:9], 0, v[10:11]
	global_load_dwordx4 v[8:11], v[6:7], off
	global_load_dwordx4 v[12:15], v[6:7], off offset:-16
	v_lshl_add_u64 v[38:39], v[38:39], 0, s[20:21]
	v_cmp_lt_u64_e32 vcc, s[48:49], v[38:39]
	v_lshl_add_u64 v[2:3], v[2:3], 0, s[10:11]
	v_lshl_add_u64 v[6:7], v[6:7], 0, s[0:1]
	s_or_b64 s[14:15], vcc, s[14:15]
	s_waitcnt vmcnt(0)
	v_cvt_pk_bf16_f32 v12, v12, v13
	v_cvt_pk_bf16_f32 v13, v14, v15
	v_cvt_pk_bf16_f32 v14, v8, v9
	v_cvt_pk_bf16_f32 v15, v10, v11
	global_store_dwordx4 v[16:17], v[12:15], off nt
	s_andn2_b64 exec, exec, s[14:15]
	s_cbranch_execnz .LBB0_239
